# k=5 rwkv_out_rows: loop-invariant parameter quads staged once in the wave's LDS slice (ds_read instead of 14 global loads per item); next-item prefetch waited only at the register hand-over
# speedup vs baseline: 1.0125x; 1.0125x over previous
; __device__ __forceinline__ void rwkv_out_rows(CArgs& a, int l, int nrows, int gw, int ngw, int lane) {
;     const bf16_t* RW = (const bf16_t*)(a.ws + WS_RW); const bf16_t* Y0 = (const bf16_t*)(a.ws + WS_H); bf16_t* Y1 = (bf16_t*)(a.ws + WS_Y1);
;     const bf16_t* A0 = (const bf16_t*)(a.ws + WS_AA0); const bf16_t* A1 = (const bf16_t*)(a.ws + WS_AA1); const bf16_t* G = (const bf16_t*)(a.ws + WS_G);
;     const float* mu = a.in[16] + l * 3488;
;     ...
;     u32x4 R[14], N[14];
; #pragma unroll
;     for (int i = 0; i < 14; ++i) { R[i] = (u32x4){0u, 0u, 0u, 0u}; N[i] = R[i]; }
;     int it = gw;
;     if (it < 2 * nrows) RO_LOAD(R, it);
;     ...
;             float xp[8], x[8], xn[8], m[8]; un8(R[5 + 3 * X], xp); un8(R[6 + 3 * X], x); un8(R[7 + 3 * X], xn); ld8f(mu + X * 1024 + c0, m);
; #pragma unroll
;             for (int j = 0; j < 8; ++j) z[X][j] = x[j] + m[j] * ((mp * xp[j] + mn * xn[j]) - x[j]);
;         }
;         ld8f(a.in[25] + l * 1024 + c0, lnw); ld8f(a.in[26] + l * 1024 + c0, lnb); ld8f(a.in[23] + l * 1024 + c0, ka); ld8f(a.in[24] + l * 1024 + c0, rk);
.LBB0_286:
	s_and_b64 vcc, exec, s[4:5]
	s_cbranch_vccz .LBB0_294
	v_readlane_b32 s1, v255, 49
	s_lshl_b32 s1, s1, 1
	v_readlane_b32 s4, v255, 50
	s_cmp_ge_i32 s4, s1
	v_readlane_b32 s5, v255, 51
	s_cbranch_scc1 .LBB0_294
	s_load_dwordx2 s[16:17], s[74:75], 0x110
	s_load_dwordx2 s[10:11], s[74:75], 0x80
	s_mul_i32 s4, s62, 0xda0
	v_readlane_b32 s34, v255, 50
	v_lshlrev_b32_e32 v179, 3, v180
	s_waitcnt lgkmcnt(0)
	s_add_u32 s3, s16, 0x11200000
	s_addc_u32 s6, s17, 0
	s_add_u32 s40, s16, 0x29e00000
	s_addc_u32 s41, s17, 0
	s_add_u32 s42, s16, 0x25600000
	s_addc_u32 s43, s17, 0
	s_ashr_i32 s5, s4, 31
	s_add_u32 s44, s16, 0x23200000
	s_addc_u32 s45, s17, 0
	s_add_u32 s48, s16, 0x27a00000
	s_addc_u32 s49, s17, 0
	s_lshl_b64 s[4:5], s[4:5], 2
	s_add_u32 s50, s10, s4
	s_addc_u32 s51, s11, s5
	v_readlane_b32 s5, v255, 42
	s_lshl_b32 s7, s5, 9
	s_ashr_i32 s4, s34, 1
	s_and_b32 s5, s7, 0x200
	v_or_b32_e32 v0, s5, v179
	s_cmpk_lt_i32 s4, 0x4000
	s_movk_i32 s5, 0x7ff
	s_cselect_b32 s14, s5, 0xff
	s_and_b32 s18, s14, s4
	s_ashr_i32 s5, s4, 31
	s_mul_i32 s10, s4, 0x1c00
	s_mul_hi_i32 s11, s4, 0x1c00
	s_add_u32 s10, s3, s10
	s_addc_u32 s11, s6, s11
	s_cmp_eq_u32 s18, 0
	s_cselect_b32 s17, 0, -1
	s_cselect_b32 s16, 0, 0xffffe400
	s_cmp_eq_u32 s18, s14
	v_lshlrev_b32_e32 v0, 1, v0
	s_cselect_b32 s18, 0, 0x1c00
	s_lshl_b64 s[4:5], s[4:5], 11
	s_waitcnt vmcnt(0)
	v_or_b32_e32 v4, s4, v0
	v_mov_b32_e32 v5, s5
	v_lshl_add_u64 v[6:7], s[88:89], 0, v[4:5]
	v_lshl_add_u64 v[8:9], s[40:41], 0, v[4:5]
	v_lshl_add_u64 v[2:3], s[10:11], 0, v[0:1]
	global_load_dwordx4 v[48:51], v[6:7], off
	global_load_dwordx4 v[32:35], v[8:9], off
	v_lshl_add_u64 v[6:7], s[48:49], 0, v[4:5]
	v_lshl_add_u64 v[8:9], s[44:45], 0, v[4:5]
	v_lshl_add_u64 v[4:5], s[42:43], 0, v[4:5]
	global_load_dwordx4 v[40:43], v[6:7], off
	global_load_dwordx4 v[104:107], v[8:9], off
	v_lshl_add_u64 v[6:7], v[2:3], 0, s[16:17]
	global_load_dwordx4 v[108:111], v[4:5], off
	global_load_dwordx4 v[88:91], v[6:7], off
	v_lshl_add_u64 v[4:5], v[2:3], 0, s[18:19]
	s_mov_b64 s[4:5], 0x1000
	global_load_dwordx4 v[96:99], v[4:5], off
	global_load_dwordx4 v[84:87], v[6:7], off offset:2048
	global_load_dwordx4 v[112:115], v0, s[10:11]
	global_load_dwordx4 v[100:103], v0, s[10:11] offset:2048
	v_lshl_add_u64 v[6:7], v[2:3], 0, s[4:5]
	s_movk_i32 s4, 0x1000
	v_add_co_u32_e32 v2, vcc, s4, v2
	v_lshl_add_u64 v[8:9], v[6:7], 0, s[16:17]
	s_nop 0
	v_addc_co_u32_e32 v3, vcc, 0, v3, vcc
	global_load_dwordx4 v[92:95], v[4:5], off offset:2048
	global_load_dwordx4 v[64:67], v[8:9], off
	v_lshl_add_u64 v[4:5], v[6:7], 0, s[18:19]
	global_load_dwordx4 v[80:83], v[2:3], off
	global_load_dwordx4 v[76:79], v[4:5], off
	s_load_dwordx8 s[56:63], s[74:75], 0xb8
	v_readlane_b32 s4, v255, 43
	v_readlane_b32 s5, v255, 44
	s_lshl_b32 s4, s4, 10
	s_ashr_i32 s5, s4, 31
	s_lshl_b64 s[4:5], s[4:5], 2
	s_waitcnt lgkmcnt(0)
	s_add_u32 s52, s60, s4
	s_addc_u32 s53, s61, s5
	s_add_u32 s54, s62, s4
	s_addc_u32 s55, s63, s5
	s_add_u32 s56, s56, s4
	s_addc_u32 s57, s57, s5
	s_add_u32 s58, s58, s4
	v_mov_b32_e32 v2, v1
	v_mov_b32_e32 v3, v1
	v_readlane_b32 s62, v255, 43
	s_addc_u32 s59, s59, s5
	s_lshl_b32 s4, s2, 12
	v_mov_b32_e32 v0, v1
	v_mov_b64_e32 v[6:7], v[2:3]
	v_mov_b64_e32 v[10:11], v[2:3]
	v_mov_b64_e32 v[14:15], v[2:3]
	v_mov_b64_e32 v[18:19], v[2:3]
	v_mov_b64_e32 v[22:23], v[2:3]
	v_mov_b64_e32 v[26:27], v[2:3]
	v_mov_b64_e32 v[38:39], v[2:3]
	v_mov_b64_e32 v[30:31], v[2:3]
	v_mov_b64_e32 v[46:47], v[2:3]
	v_mov_b64_e32 v[54:55], v[2:3]
	v_mov_b64_e32 v[58:59], v[2:3]
	v_mov_b64_e32 v[62:63], v[2:3]
	v_mov_b64_e32 v[70:71], v[2:3]
	v_mov_b64_e32 v[74:75], v[2:3]
	v_readlane_b32 s63, v255, 44
	s_add_i32 s7, s4, s7
	s_lshl_b32 s10, s0, 12
	v_mov_b64_e32 v[4:5], v[0:1]
	v_mov_b64_e32 v[8:9], v[0:1]
	v_mov_b64_e32 v[12:13], v[0:1]
	v_mov_b64_e32 v[16:17], v[0:1]
	v_mov_b64_e32 v[20:21], v[0:1]
	v_mov_b64_e32 v[24:25], v[0:1]
	v_mov_b64_e32 v[36:37], v[0:1]
	v_mov_b64_e32 v[28:29], v[0:1]
	v_mov_b64_e32 v[44:45], v[0:1]
	v_mov_b64_e32 v[52:53], v[0:1]
	v_mov_b64_e32 v[56:57], v[0:1]
	v_mov_b64_e32 v[60:61], v[0:1]
	v_mov_b64_e32 v[68:69], v[0:1]
	v_mov_b64_e32 v[72:73], v[0:1]
	s_mov_b32 s14, s34
	v_readlane_b32 s35, v255, 51
	v_readlane_b32 s4, v255, 42
	s_and_b32 s5, s7, 0x200
	s_nop 1
	s_mul_i32 s4, s4, 0x3800
	v_or_b32_e32 v175, s5, v179
	v_lshlrev_b32_e32 v175, 2, v175
	v_lshl_add_u32 v174, v180, 4, s4
	s_add_u32 s4, s50, 0x1000
	s_addc_u32 s5, s51, 0
	s_add_u32 s16, s50, 0x2000
	s_addc_u32 s17, s51, 0
	global_load_dwordx4 v[222:225], v175, s[50:51]
	global_load_dwordx4 v[226:229], v175, s[50:51] offset:16
	global_load_dwordx4 v[230:233], v175, s[4:5]
	global_load_dwordx4 v[234:237], v175, s[4:5] offset:16
	global_load_dwordx4 v[238:241], v175, s[16:17]
	global_load_dwordx4 v[242:245], v175, s[16:17] offset:16
	global_load_dwordx4 v[246:249], v175, s[56:57]
	global_load_dwordx4 v[250:253], v175, s[56:57] offset:16
	s_waitcnt vmcnt(0)
	ds_write_b128 v174, v[222:225]
	ds_write_b128 v174, v[226:229] offset:1024
	ds_write_b128 v174, v[230:233] offset:2048
	ds_write_b128 v174, v[234:237] offset:3072
	ds_write_b128 v174, v[238:241] offset:4096
	ds_write_b128 v174, v[242:245] offset:5120
	ds_write_b128 v174, v[246:249] offset:6144
	ds_write_b128 v174, v[250:253] offset:7168
	s_waitcnt lgkmcnt(0)
	global_load_dwordx4 v[222:225], v175, s[58:59]
	global_load_dwordx4 v[226:229], v175, s[58:59] offset:16
	global_load_dwordx4 v[230:233], v175, s[52:53]
	global_load_dwordx4 v[234:237], v175, s[52:53] offset:16
	global_load_dwordx4 v[238:241], v175, s[54:55]
	global_load_dwordx4 v[242:245], v175, s[54:55] offset:16
	s_waitcnt vmcnt(0)
	ds_write_b128 v174, v[222:225] offset:8192
	ds_write_b128 v174, v[226:229] offset:9216
	ds_write_b128 v174, v[230:233] offset:10240
	ds_write_b128 v174, v[234:237] offset:11264
	ds_write_b128 v174, v[238:241] offset:12288
	ds_write_b128 v174, v[242:245] offset:13312
	s_waitcnt lgkmcnt(0)
	s_branch .LBB0_290
; __device__ __forceinline__ void rwkv_out_rows(CArgs& a, int l, int nrows, int gw, int ngw, int lane) {
;     ...
;         const int row = it >> 1, c0 = (it & 1) * 512 + 8 * lane;
;         int t, Tn; if (row < ML) { t = row & 2047; Tn = 2048; } else { t = (row - ML) & 255; Tn = 256; }
;         const float mp = t > 0 ? 0.5f : 0.f, mn = t < Tn - 1 ? 0.5f : 0.f;
;         float y[8], y1[8], g[8], a0[8], a1[8], z[3][8], lnw[8], lnb[8], ka[8], rk[8];
;         un8(R[0], y); un8(R[1], y1); un8(R[2], g); un8(R[3], a0); un8(R[4], a1);
; #pragma unroll
;         for (int X = 0; X < 3; ++X) {
;             float xp[8], x[8], xn[8], m[8]; un8(R[5 + 3 * X], xp); un8(R[6 + 3 * X], x); un8(R[7 + 3 * X], xn); ld8f(mu + X * 1024 + c0, m);
; #pragma unroll
;             for (int j = 0; j < 8; ++j) z[X][j] = x[j] + m[j] * ((mp * xp[j] + mn * xn[j]) - x[j]);
;         }
;         ld8f(a.in[25] + l * 1024 + c0, lnw); ld8f(a.in[26] + l * 1024 + c0, lnb); ld8f(a.in[23] + l * 1024 + c0, ka); ld8f(a.in[24] + l * 1024 + c0, rk);
;         float sm = 0.f;
; #pragma unroll
;         for (int j = 0; j < 8; ++j) { y[j] += y1[j]; sm += y[j]; }
;         const float mean = dpp_sum8(sm) * (1.f / 64.f);
;         float sv = 0.f, sb = 0.f;
; #pragma unroll
;         for (int j = 0; j < 8; ++j) { y[j] -= mean; sv += y[j] * y[j]; const float kds = z[1][j] * ((1.f + (a0[j] - 1.f) * ka[j]) + (1.f + (a1[j] - 1.f) * ka[j])); sb += z[0][j] * kds * rk[j]; }
.LBB0_289:
	v_lshlrev_b64 v[120:121], 2, v[0:1]
	v_lshl_add_u64 v[122:123], s[50:51], 0, v[120:121]
	s_mov_b64 s[4:5], 0x2000
	v_lshl_add_u64 v[124:125], s[56:57], 0, v[120:121]
	v_add_co_u32_e32 v136, vcc, s93, v122
	v_lshl_add_u64 v[2:3], v[122:123], 0, s[4:5]
	ds_read_b128 v[160:163], v174 offset:6144
	v_addc_co_u32_e32 v137, vcc, 0, v123, vcc
	ds_read_b128 v[140:143], v174
	ds_read_b128 v[116:119], v174 offset:5120
	ds_read_b128 v[148:151], v174 offset:2048
	v_lshl_add_u64 v[126:127], s[58:59], 0, v[120:121]
	ds_read_b128 v[144:147], v174 offset:8192
	ds_read_b128 v[156:159], v174 offset:1024
	ds_read_b128 v[168:171], v174 offset:7168
	ds_read_b128 v[152:155], v174 offset:9216
	s_mov_b64 s[16:17], 0x1000
	s_waitcnt lgkmcnt(0)
	v_lshlrev_b32_e32 v128, 16, v51
	v_and_b32_e32 v129, 0xffff0000, v51
	v_lshlrev_b32_e32 v130, 16, v35
	v_and_b32_e32 v131, 0xffff0000, v35
	v_and_b32_e32 v133, 0xffff0000, v104
	v_lshlrev_b32_e32 v132, 16, v104
	v_and_b32_e32 v135, 0xffff0000, v108
	v_lshlrev_b32_e32 v134, 16, v108
	v_and_b32_e32 v217, 0xffff0000, v105
	v_lshlrev_b32_e32 v216, 16, v105
	v_lshl_add_u64 v[104:105], s[52:53], 0, v[120:121]
	v_lshl_add_u64 v[164:165], v[122:123], 0, s[16:17]
	v_lshl_add_u64 v[138:139], s[54:55], 0, v[120:121]
	v_pk_add_f32 v[182:183], v[128:129], v[130:131]
	v_pk_add_f32 v[218:219], v[132:133], -1.0 op_sel_hi:[1,0]
	v_pk_add_f32 v[220:221], v[134:135], -1.0 op_sel_hi:[1,0]
	ds_read_b128 v[120:123], v174 offset:11264
	ds_read_b128 v[128:131], v174 offset:10240
	ds_read_b128 v[124:127], v174 offset:13312
	ds_read_b128 v[132:135], v174 offset:12288
	s_nop 0
	ds_read_b128 v[164:167], v174 offset:3072
	s_ashr_i32 s4, s14, 1
	ds_read_b128 v[136:139], v174 offset:4096
	s_cmpk_lt_i32 s4, 0x4000
	s_movk_i32 s5, 0x7ff
	s_cselect_b32 s5, s5, 0xff
	s_and_b32 s14, s5, s4
	s_cmp_eq_u32 s14, s5
	s_cselect_b64 s[16:17], -1, 0
	s_cmp_eq_u32 s14, 0
	v_cndmask_b32_e64 v184, 0.5, 0, s[16:17]
	s_cselect_b64 s[16:17], -1, 0
	v_lshlrev_b32_e32 v202, 16, v67
	v_and_b32_e32 v203, 0xffff0000, v79
	v_and_b32_e32 v207, 0xffff0000, v88
	v_lshlrev_b32_e32 v206, 16, v96
	v_and_b32_e32 v213, 0xffff0000, v84
	v_lshlrev_b32_e32 v212, 16, v92
	v_cndmask_b32_e64 v185, 0.5, 0, s[16:17]
	v_lshlrev_b32_e32 v200, 16, v79
	v_and_b32_e32 v201, 0xffff0000, v67
	v_and_b32_e32 v209, 0xffff0000, v96
	v_lshlrev_b32_e32 v208, 16, v88
	v_and_b32_e32 v215, 0xffff0000, v92
	v_lshlrev_b32_e32 v214, 16, v84
	v_pk_mul_f32 v[104:105], v[184:185], v[202:203] op_sel:[1,0] op_sel_hi:[0,1]
	v_pk_mul_f32 v[202:203], v[184:185], v[206:207]
	v_pk_mul_f32 v[206:207], v[184:185], v[212:213]
	v_lshlrev_b32_e32 v198, 16, v83
	v_and_b32_e32 v199, 0xffff0000, v83
	v_and_b32_e32 v211, 0xffff0000, v100
	v_lshlrev_b32_e32 v210, 16, v100
	v_pk_fma_f32 v[104:105], v[184:185], v[200:201], v[104:105]
	v_pk_fma_f32 v[200:201], v[184:185], v[208:209], v[202:203] op_sel:[1,0,0] op_sel_hi:[0,1,1]
	v_pk_fma_f32 v[202:203], v[184:185], v[214:215], v[206:207] op_sel:[1,0,0] op_sel_hi:[0,1,1]
	v_and_b32_e32 v205, 0xffff0000, v112
	v_lshlrev_b32_e32 v204, 16, v112
	v_pk_add_f32 v[104:105], v[104:105], v[198:199] neg_lo:[0,1] neg_hi:[0,1]
	v_pk_add_f32 v[202:203], v[202:203], v[210:211] neg_lo:[0,1] neg_hi:[0,1]
	v_pk_add_f32 v[200:201], v[200:201], v[204:205] neg_lo:[0,1] neg_hi:[0,1]
	v_lshlrev_b32_e32 v108, 16, v113
	v_lshlrev_b32_e32 v96, 16, v89
	v_lshlrev_b32_e32 v88, 16, v101
	v_lshlrev_b32_e32 v100, 16, v93
	v_lshlrev_b32_e32 v112, 16, v97
	v_and_b32_e32 v93, 0xffff0000, v93
	v_lshlrev_b32_e32 v92, 16, v85
	v_and_b32_e32 v97, 0xffff0000, v97
	v_and_b32_e32 v83, 0xffff0000, v66
	v_lshlrev_b32_e32 v66, 16, v66
	v_and_b32_e32 v67, 0xffff0000, v78
	v_lshlrev_b32_e32 v2, 16, v43
	v_and_b32_e32 v3, 0xffff0000, v43
	v_and_b32_e32 v51, 0xffff0000, v34
	v_pk_fma_f32 v[206:207], v[218:219], v[160:161], 1.0 op_sel_hi:[1,1,0]
	v_pk_fma_f32 v[160:161], v[220:221], v[160:161], 1.0 op_sel_hi:[1,1,0]
	v_and_b32_e32 v43, 0xffff0000, v82
	v_pk_fma_f32 v[140:141], v[200:201], v[140:141], v[204:205]
	v_pk_fma_f32 v[104:105], v[104:105], v[118:119], v[198:199]
	v_pk_add_f32 v[118:119], v[206:207], v[160:161]
	v_pk_fma_f32 v[148:149], v[202:203], v[148:149], v[210:211]
	v_pk_mul_f32 v[66:67], v[184:185], v[66:67] op_sel:[1,0] op_sel_hi:[0,1]
	v_pk_mul_f32 v[118:119], v[148:149], v[118:119]
	v_and_b32_e32 v79, 0xffff0000, v33
	v_pk_mul_f32 v[118:119], v[140:141], v[118:119]
	s_ashr_i32 s5, s4, 31
	v_pk_mul_f32 v[118:119], v[144:145], v[118:119]
	s_lshl_b64 s[4:5], s[4:5], 11
	v_add_f32_e32 v35, 0, v118
	v_add_f32_e32 v35, v119, v35
	v_and_b32_e32 v119, 0xffff0000, v109
	v_lshlrev_b32_e32 v118, 16, v109
	v_and_b32_e32 v109, 0xffff0000, v113
	v_and_b32_e32 v113, 0xffff0000, v89
	v_and_b32_e32 v89, 0xffff0000, v101
	v_and_b32_e32 v101, 0xffff0000, v85
	v_pk_mul_f32 v[100:101], v[184:185], v[100:101]
	v_pk_add_f32 v[84:85], v[216:217], -1.0 op_sel_hi:[1,0]
	v_pk_add_f32 v[118:119], v[118:119], -1.0 op_sel_hi:[1,0]
	v_pk_mul_f32 v[112:113], v[184:185], v[112:113]
	v_pk_fma_f32 v[92:93], v[184:185], v[92:93], v[100:101] op_sel:[1,0,0] op_sel_hi:[0,1,1]
	v_pk_fma_f32 v[84:85], v[84:85], v[162:163], 1.0 op_sel_hi:[1,1,0]
	v_pk_fma_f32 v[118:119], v[118:119], v[162:163], 1.0 op_sel_hi:[1,1,0]
	v_pk_fma_f32 v[96:97], v[184:185], v[96:97], v[112:113] op_sel:[1,0,0] op_sel_hi:[0,1,1]
	v_pk_add_f32 v[92:93], v[92:93], v[88:89] neg_lo:[0,1] neg_hi:[0,1]
	v_pk_add_f32 v[84:85], v[84:85], v[118:119]
	v_pk_add_f32 v[96:97], v[96:97], v[108:109] neg_lo:[0,1] neg_hi:[0,1]
	v_pk_fma_f32 v[88:89], v[92:93], v[150:151], v[88:89]
	v_pk_fma_f32 v[96:97], v[96:97], v[142:143], v[108:109]
	v_pk_mul_f32 v[84:85], v[88:89], v[84:85]
; __device__ __forceinline__ void rwkv_out_rows(CArgs& a, int l, int nrows, int gw, int ngw, int lane) {
;     ...
;         ld8f(a.in[25] + l * 1024 + c0, lnw); ld8f(a.in[26] + l * 1024 + c0, lnb); ld8f(a.in[23] + l * 1024 + c0, ka); ld8f(a.in[24] + l * 1024 + c0, rk);
;         float sm = 0.f;
; #pragma unroll
;         for (int j = 0; j < 8; ++j) { y[j] += y1[j]; sm += y[j]; }
;         const float mean = dpp_sum8(sm) * (1.f / 64.f);
;         float sv = 0.f, sb = 0.f;
; #pragma unroll
;         for (int j = 0; j < 8; ++j) { y[j] -= mean; sv += y[j] * y[j]; const float kds = z[1][j] * ((1.f + (a0[j] - 1.f) * ka[j]) + (1.f + (a1[j] - 1.f) * ka[j])); sb += z[0][j] * kds * rk[j]; }
;         const float rstd = rsqrtf(dpp_sum8(sv) * (1.f / 64.f) + 64e-5f), bsum = dpp_sum8(sb);
	v_and_b32_e32 v89, 0xffff0000, v110
	v_pk_mul_f32 v[84:85], v[96:97], v[84:85]
	v_lshlrev_b32_e32 v88, 16, v110
	v_pk_mul_f32 v[84:85], v[146:147], v[84:85]
	v_pk_add_f32 v[88:89], v[88:89], -1.0 op_sel_hi:[1,0]
	v_add_f32_e32 v35, v84, v35
	v_add_f32_e32 v35, v85, v35
	v_and_b32_e32 v85, 0xffff0000, v106
	v_lshlrev_b32_e32 v84, 16, v106
	v_pk_add_f32 v[84:85], v[84:85], -1.0 op_sel_hi:[1,0]
	v_and_b32_e32 v97, 0xffff0000, v90
	v_lshlrev_b32_e32 v96, 16, v98
	v_pk_fma_f32 v[84:85], v[84:85], v[168:169], 1.0 op_sel_hi:[1,1,0]
	v_pk_fma_f32 v[88:89], v[88:89], v[168:169], 1.0 op_sel_hi:[1,1,0]
	v_and_b32_e32 v101, 0xffff0000, v98
	v_lshlrev_b32_e32 v100, 16, v90
	v_pk_add_f32 v[84:85], v[84:85], v[88:89]
	v_pk_mul_f32 v[88:89], v[184:185], v[96:97]
	v_and_b32_e32 v93, 0xffff0000, v114
	v_lshlrev_b32_e32 v92, 16, v114
	v_pk_fma_f32 v[88:89], v[184:185], v[100:101], v[88:89] op_sel:[1,0,0] op_sel_hi:[0,1,1]
	v_and_b32_e32 v113, 0xffff0000, v86
	v_lshlrev_b32_e32 v112, 16, v94
	v_pk_add_f32 v[88:89], v[88:89], v[92:93] neg_lo:[0,1] neg_hi:[0,1]
	v_and_b32_e32 v119, 0xffff0000, v94
	v_lshlrev_b32_e32 v118, 16, v86
	v_pk_fma_f32 v[88:89], v[88:89], v[156:157], v[92:93]
	v_pk_mul_f32 v[92:93], v[184:185], v[112:113]
	v_and_b32_e32 v109, 0xffff0000, v102
	v_lshlrev_b32_e32 v108, 16, v102
	v_pk_fma_f32 v[92:93], v[184:185], v[118:119], v[92:93] op_sel:[1,0,0] op_sel_hi:[0,1,1]
	v_pk_add_f32 v[92:93], v[92:93], v[108:109] neg_lo:[0,1] neg_hi:[0,1]
	v_and_b32_e32 v101, 0xffff0000, v87
	s_waitcnt lgkmcnt(1)
	v_pk_fma_f32 v[92:93], v[92:93], v[164:165], v[108:109]
	v_lshlrev_b32_e32 v100, 16, v95
	v_pk_mul_f32 v[84:85], v[92:93], v[84:85]
	v_lshlrev_b32_e32 v94, 16, v87
	v_pk_mul_f32 v[84:85], v[88:89], v[84:85]
	v_and_b32_e32 v89, 0xffff0000, v111
	v_pk_mul_f32 v[84:85], v[152:153], v[84:85]
	v_lshlrev_b32_e32 v88, 16, v111
	v_add_f32_e32 v35, v84, v35
	v_add_f32_e32 v35, v85, v35
	v_and_b32_e32 v85, 0xffff0000, v107
	v_lshlrev_b32_e32 v84, 16, v107
	v_pk_add_f32 v[84:85], v[84:85], -1.0 op_sel_hi:[1,0]
	v_pk_add_f32 v[86:87], v[88:89], -1.0 op_sel_hi:[1,0]
	v_and_b32_e32 v97, 0xffff0000, v91
	v_lshlrev_b32_e32 v96, 16, v99
	v_and_b32_e32 v95, 0xffff0000, v95
	v_pk_fma_f32 v[84:85], v[84:85], v[170:171], 1.0 op_sel_hi:[1,1,0]
	v_pk_fma_f32 v[86:87], v[86:87], v[170:171], 1.0 op_sel_hi:[1,1,0]
	v_pk_mul_f32 v[88:89], v[184:185], v[100:101]
	v_and_b32_e32 v99, 0xffff0000, v99
	v_lshlrev_b32_e32 v98, 16, v91
	v_and_b32_e32 v91, 0xffff0000, v103
	v_lshlrev_b32_e32 v90, 16, v103
	v_pk_add_f32 v[84:85], v[84:85], v[86:87]
	v_pk_mul_f32 v[86:87], v[184:185], v[96:97]
	v_pk_fma_f32 v[88:89], v[184:185], v[94:95], v[88:89] op_sel:[1,0,0] op_sel_hi:[0,1,1]
	v_and_b32_e32 v93, 0xffff0000, v115
	v_lshlrev_b32_e32 v92, 16, v115
	v_pk_fma_f32 v[86:87], v[184:185], v[98:99], v[86:87] op_sel:[1,0,0] op_sel_hi:[0,1,1]
	v_pk_add_f32 v[88:89], v[88:89], v[90:91] neg_lo:[0,1] neg_hi:[0,1]
	v_pk_add_f32 v[86:87], v[86:87], v[92:93] neg_lo:[0,1] neg_hi:[0,1]
	v_pk_fma_f32 v[88:89], v[88:89], v[166:167], v[90:91]
	v_pk_fma_f32 v[86:87], v[86:87], v[158:159], v[92:93]
	v_pk_mul_f32 v[84:85], v[88:89], v[84:85]
	v_lshlrev_b32_e32 v90, 16, v65
	v_pk_mul_f32 v[84:85], v[86:87], v[84:85]
	v_lshlrev_b32_e32 v86, 16, v50
	v_pk_mul_f32 v[84:85], v[154:155], v[84:85]
	v_and_b32_e32 v87, 0xffff0000, v50
	v_add_f32_e32 v35, v84, v35
	v_add_f32_e32 v35, v85, v35
	v_lshlrev_b32_e32 v50, 16, v34
	v_lshlrev_b32_e32 v34, 16, v42
	v_add_f32_dpp v35, v35, v35 quad_perm:[1,0,3,2] row_mask:0xf bank_mask:0xf bound_ctrl:1
	v_and_b32_e32 v91, 0xffff0000, v77
	v_lshlrev_b32_e32 v88, 16, v77
	v_add_f32_dpp v35, v35, v35 quad_perm:[2,3,0,1] row_mask:0xf bank_mask:0xf bound_ctrl:1
	v_and_b32_e32 v89, 0xffff0000, v65
	v_pk_add_f32 v[50:51], v[86:87], v[50:51]
	v_add_f32_dpp v84, v35, v35 row_half_mirror row_mask:0xf bank_mask:0xf bound_ctrl:1
	v_and_b32_e32 v35, 0xffff0000, v42
	v_lshlrev_b32_e32 v42, 16, v82
	v_lshlrev_b32_e32 v82, 16, v78
	v_pk_fma_f32 v[66:67], v[184:185], v[82:83], v[66:67]
	v_lshlrev_b32_e32 v78, 16, v33
	v_pk_add_f32 v[66:67], v[66:67], v[42:43] neg_lo:[0,1] neg_hi:[0,1]
	v_lshlrev_b32_e32 v86, 16, v81
	v_pk_fma_f32 v[42:43], v[66:67], v[116:117], v[42:43]
	v_lshlrev_b32_e32 v66, 16, v49
	v_and_b32_e32 v67, 0xffff0000, v49
	v_pk_add_f32 v[66:67], v[66:67], v[78:79]
	v_pk_mul_f32 v[78:79], v[184:185], v[90:91] op_sel:[1,0] op_sel_hi:[0,1]
	v_and_b32_e32 v87, 0xffff0000, v81
	v_pk_fma_f32 v[78:79], v[184:185], v[88:89], v[78:79]
	v_and_b32_e32 v49, 0xffff0000, v32
	v_pk_add_f32 v[78:79], v[78:79], v[86:87] neg_lo:[0,1] neg_hi:[0,1]
	v_lshlrev_b32_e32 v82, 16, v41
	s_waitcnt lgkmcnt(0)
; __device__ __forceinline__ unsigned pkbf(float lo, float hi) { f32x2 v = {lo, hi}; bf16x2v b = __builtin_convertvector(v, bf16x2v); return __builtin_bit_cast(unsigned, b); }
; __device__ __forceinline__ void rwkv_out_rows(CArgs& a, int l, int nrows, int gw, int ngw, int lane) {
;     ...
;         const float mean = dpp_sum8(sm) * (1.f / 64.f);
;         float sv = 0.f, sb = 0.f;
; #pragma unroll
;         for (int j = 0; j < 8; ++j) { y[j] -= mean; sv += y[j] * y[j]; const float kds = z[1][j] * ((1.f + (a0[j] - 1.f) * ka[j]) + (1.f + (a1[j] - 1.f) * ka[j])); sb += z[0][j] * kds * rk[j]; }
;         const float rstd = rsqrtf(dpp_sum8(sv) * (1.f / 64.f) + 64e-5f), bsum = dpp_sum8(sb);
;         u32x4 o;
; #pragma unroll
;         for (int j = 0; j < 4; ++j) o[j] = pkbf(((y[2 * j] * rstd * lnw[2 * j] + lnb[2 * j]) + bsum * z[2][2 * j]) * g[2 * j], ((y[2 * j + 1] * rstd * lnw[2 * j + 1] + lnb[2 * j + 1]) + bsum * z[2][2 * j + 1]) * g[2 * j + 1]);
;         *(u32x4*)(Y1 + (size_t)row * 1024 + c0) = o;
; #pragma unroll
;         for (int i = 0; i < 14; ++i) R[i] = N[i];
	v_pk_fma_f32 v[78:79], v[78:79], v[138:139], v[86:87]
	v_lshlrev_b32_e32 v86, 16, v48
	v_and_b32_e32 v87, 0xffff0000, v48
	v_lshlrev_b32_e32 v48, 16, v32
	v_pk_add_f32 v[48:49], v[86:87], v[48:49]
	v_and_b32_e32 v83, 0xffff0000, v41
	v_lshlrev_b32_e32 v32, 16, v40
	v_and_b32_e32 v33, 0xffff0000, v40
	v_lshlrev_b32_e32 v40, 16, v80
	v_and_b32_e32 v41, 0xffff0000, v80
	v_lshlrev_b32_e32 v80, 16, v76
	v_and_b32_e32 v65, 0xffff0000, v76
	v_add_f32_e32 v76, 0, v48
	v_add_f32_e32 v76, v49, v76
	v_add_f32_e32 v76, v66, v76
	v_add_f32_e32 v76, v67, v76
	v_add_f32_e32 v76, v50, v76
	v_add_f32_e32 v76, v51, v76
	v_add_f32_e32 v76, v182, v76
	v_add_f32_e32 v76, v183, v76
	v_and_b32_e32 v81, 0xffff0000, v64
	v_lshlrev_b32_e32 v64, 16, v64
	v_add_f32_dpp v76, v76, v76 quad_perm:[1,0,3,2] row_mask:0xf bank_mask:0xf bound_ctrl:1
	v_pk_mul_f32 v[64:65], v[184:185], v[64:65] op_sel:[1,0] op_sel_hi:[0,1]
	v_pk_fma_f32 v[64:65], v[184:185], v[80:81], v[64:65]
	v_add_f32_dpp v76, v76, v76 quad_perm:[2,3,0,1] row_mask:0xf bank_mask:0xf bound_ctrl:1
	v_pk_add_f32 v[64:65], v[64:65], v[40:41] neg_lo:[0,1] neg_hi:[0,1]
	s_add_u32 s4, s40, s4
	v_add_f32_dpp v76, v76, v76 row_half_mirror row_mask:0xf bank_mask:0xf bound_ctrl:1
	v_mul_f32_e32 v76, 0x3c800000, v76
	v_pk_add_f32 v[48:49], v[48:49], v[76:77] op_sel_hi:[1,0] neg_lo:[0,1] neg_hi:[0,1]
	v_pk_add_f32 v[66:67], v[66:67], v[76:77] op_sel_hi:[1,0] neg_lo:[0,1] neg_hi:[0,1]
	v_pk_mul_f32 v[86:87], v[48:49], v[48:49]
	v_pk_mul_f32 v[88:89], v[66:67], v[66:67]
	v_add_f32_e32 v85, v86, v87
	v_pk_add_f32 v[50:51], v[50:51], v[76:77] op_sel_hi:[1,0] neg_lo:[0,1] neg_hi:[0,1]
	v_add_f32_e32 v85, v88, v85
	v_pk_mul_f32 v[90:91], v[50:51], v[50:51]
	v_add_f32_e32 v85, v89, v85
	v_pk_add_f32 v[76:77], v[182:183], v[76:77] op_sel_hi:[1,0] neg_lo:[0,1] neg_hi:[0,1]
	v_add_f32_e32 v85, v90, v85
	v_pk_mul_f32 v[92:93], v[76:77], v[76:77]
	v_add_f32_e32 v85, v91, v85
	v_add_f32_e32 v85, v92, v85
	v_add_f32_e32 v85, v93, v85
	v_mov_b32_e32 v86, 0x3a27c5ac
	v_pk_fma_f32 v[40:41], v[64:65], v[136:137], v[40:41]
	v_add_f32_dpp v85, v85, v85 quad_perm:[1,0,3,2] row_mask:0xf bank_mask:0xf bound_ctrl:1
	s_addc_u32 s5, s41, s5
	s_waitcnt vmcnt(0)
	v_mov_b64_e32 v[110:111], v[22:23]
	v_add_f32_dpp v85, v85, v85 quad_perm:[2,3,0,1] row_mask:0xf bank_mask:0xf bound_ctrl:1
	v_mov_b64_e32 v[90:91], v[26:27]
	v_mov_b64_e32 v[114:115], v[38:39]
	v_add_f32_dpp v85, v85, v85 row_half_mirror row_mask:0xf bank_mask:0xf bound_ctrl:1
	v_fmamk_f32 v85, v85, 0x3c800000, v86
	v_mul_f32_e32 v86, 0x4b800000, v85
	v_cmp_gt_f32_e32 vcc, s8, v85
	v_mov_b64_e32 v[98:99], v[30:31]
	v_mov_b64_e32 v[102:103], v[54:55]
	v_cndmask_b32_e32 v85, v85, v86, vcc
	v_rsq_f32_e32 v85, v85
	v_mov_b64_e32 v[94:95], v[58:59]
	s_add_i32 s7, s7, s10
	v_mov_b64_e32 v[108:109], v[20:21]
	v_mul_f32_e32 v64, 0x45800000, v85
	v_cndmask_b32_e32 v64, v85, v64, vcc
	v_pk_mul_f32 v[48:49], v[48:49], v[64:65] op_sel_hi:[1,0]
	s_and_b64 vcc, exec, s[60:61]
	v_pk_fma_f32 v[48:49], v[128:129], v[48:49], v[132:133]
	v_mov_b64_e32 v[88:89], v[24:25]
	v_pk_fma_f32 v[40:41], v[40:41], v[84:85], v[48:49] op_sel_hi:[1,0,1]
	v_mov_b64_e32 v[112:113], v[36:37]
	v_pk_mul_f32 v[32:33], v[40:41], v[32:33]
	v_pk_mul_f32 v[40:41], v[66:67], v[64:65] op_sel_hi:[1,0]
	v_cvt_pk_bf16_f32 v32, v32, v33
	v_pk_fma_f32 v[40:41], v[130:131], v[40:41], v[134:135]
	v_mov_b64_e32 v[96:97], v[28:29]
	v_pk_fma_f32 v[40:41], v[78:79], v[84:85], v[40:41] op_sel_hi:[1,0,1]
	v_mov_b64_e32 v[100:101], v[52:53]
	v_pk_mul_f32 v[40:41], v[40:41], v[82:83]
	v_mov_b64_e32 v[82:83], v[70:71]
	v_cvt_pk_bf16_f32 v33, v40, v41
	v_pk_mul_f32 v[40:41], v[50:51], v[64:65] op_sel_hi:[1,0]
	v_mov_b64_e32 v[50:51], v[6:7]
	v_pk_fma_f32 v[40:41], v[120:121], v[40:41], v[124:125]
	v_mov_b64_e32 v[48:49], v[4:5]
	v_pk_fma_f32 v[40:41], v[42:43], v[84:85], v[40:41] op_sel_hi:[1,0,1]
	v_mov_b64_e32 v[92:93], v[56:57]
	v_pk_mul_f32 v[34:35], v[40:41], v[34:35]
	v_pk_mul_f32 v[40:41], v[76:77], v[64:65] op_sel_hi:[1,0]
	v_cvt_pk_bf16_f32 v34, v34, v35
	v_pk_fma_f32 v[40:41], v[122:123], v[40:41], v[126:127]
	v_mov_b64_e32 v[66:67], v[62:63]
	v_pk_fma_f32 v[40:41], v[104:105], v[84:85], v[40:41] op_sel_hi:[1,0,1]
	v_mov_b64_e32 v[106:107], v[18:19]
	v_pk_mul_f32 v[2:3], v[40:41], v[2:3]
	v_mov_b64_e32 v[42:43], v[14:15]
	v_cvt_pk_bf16_f32 v35, v2, v3
	v_lshl_add_u64 v[2:3], v[0:1], 1, s[4:5]
	global_store_dwordx4 v[2:3], v[32:35], off
	v_mov_b64_e32 v[86:87], v[46:47]
	v_mov_b64_e32 v[78:79], v[74:75]
	v_mov_b64_e32 v[34:35], v[10:11]
	v_mov_b64_e32 v[32:33], v[8:9]
	v_mov_b64_e32 v[40:41], v[12:13]
	v_mov_b64_e32 v[104:105], v[16:17]
	v_mov_b64_e32 v[84:85], v[44:45]
	v_mov_b64_e32 v[64:65], v[60:61]
	v_mov_b64_e32 v[80:81], v[68:69]
	v_mov_b64_e32 v[76:77], v[72:73]
	s_mov_b32 s14, s11
	s_cbranch_vccnz .LBB0_294
